# input-projection RoPE ladder: each step's cos/sin loads issued before its eight ds_bpermute (same EXEC mask), 24 of 32 steps
# speedup vs baseline: 1.0285x; 1.0285x over previous
.LBB0_165:
	v_mov_b64_e32 v[124:125], s[76:77]
	v_mad_i64_i32 v[124:125], s[8:9], v166, s92, v[124:125]
	s_or_b32 s8, s22, 0x80
	s_cmp_lt_i32 s8, s89
	s_cselect_b64 s[8:9], -1, 0
	v_cvt_pk_bf16_f32 v134, v136, v137
	v_cvt_pk_bf16_f32 v135, v138, v139
	v_cvt_pk_bf16_f32 v136, v140, v141
	v_cvt_pk_bf16_f32 v137, v142, v143
	v_lshl_add_u64 v[124:125], v[164:165], 1, v[124:125]
	s_and_b64 s[8:9], s[30:31], s[8:9]
	global_store_dwordx4 v[124:125], v[134:137], off
	v_pk_mul_f32 v[140:141], v[114:115], v[120:121]
	s_andn2_b64 vcc, exec, s[8:9]
	v_pk_mul_f32 v[136:137], v[118:119], v[120:121]
	v_pk_mul_f32 v[134:135], v[116:117], v[168:169]
	v_pk_mul_f32 v[138:139], v[112:113], v[168:169]
	s_cbranch_vccnz .LBB0_173
	v_and_b32_e32 v121, 64, v195
	v_xor_b32_e32 v120, 16, v195
	v_add_u32_e32 v121, 64, v121
	v_cmp_lt_i32_e32 vcc, v120, v121
	s_nop 1
	v_cndmask_b32_e32 v120, v195, v120, vcc
	v_lshlrev_b32_e32 v120, 2, v120
	s_waitcnt lgkmcnt(0)
	s_and_saveexec_b64 s[98:99], s[0:1]
	v_lshlrev_b32_e32 v240, 2, v152
	global_load_dwordx4 v[198:201], v240, s[64:65]
	global_load_dwordx4 v[202:205], v240, s[44:45]
	global_load_dwordx4 v[206:209], v240, s[64:65] offset:16
	global_load_dwordx4 v[210:213], v240, s[44:45] offset:16
	s_mov_b64 exec, s[98:99]
	ds_bpermute_b32 v170, v120, v134
	ds_bpermute_b32 v174, v120, v138
	ds_bpermute_b32 v171, v120, v135
	ds_bpermute_b32 v175, v120, v139
	ds_bpermute_b32 v142, v120, v136
	ds_bpermute_b32 v178, v120, v140
	ds_bpermute_b32 v143, v120, v137
	ds_bpermute_b32 v179, v120, v141
	s_and_saveexec_b64 s[8:9], s[0:1]
	s_cbranch_execz .LBB0_172
	s_waitcnt vmcnt(0)
	v_pk_mul_f32 v[120:121], v[136:137], v[200:201]
	v_pk_mul_f32 v[130:131], v[134:135], v[198:199]
	s_waitcnt lgkmcnt(5)
	v_pk_mul_f32 v[172:173], v[202:203], v[170:171]
	s_waitcnt lgkmcnt(1)
	v_pk_mul_f32 v[176:177], v[204:205], v[142:143]
	v_pk_mul_f32 v[142:143], v[140:141], v[208:209]
	v_pk_mul_f32 v[170:171], v[138:139], v[206:207]
	v_pk_mul_f32 v[174:175], v[210:211], v[174:175]
	s_waitcnt lgkmcnt(0)
	v_pk_mul_f32 v[178:179], v[212:213], v[178:179]
	s_and_saveexec_b64 s[10:11], s[4:5]
	s_xor_b64 s[10:11], exec, s[10:11]
	v_pk_add_f32 v[136:137], v[120:121], v[176:177]
	v_pk_add_f32 v[134:135], v[130:131], v[172:173]
	v_pk_add_f32 v[140:141], v[142:143], v[178:179]
	v_pk_add_f32 v[138:139], v[170:171], v[174:175]
	s_andn2_saveexec_b64 s[10:11], s[10:11]
	v_sub_f32_e32 v137, v121, v177
	v_sub_f32_e32 v136, v120, v176
	v_sub_f32_e32 v135, v131, v173
	v_sub_f32_e32 v134, v130, v172
	v_sub_f32_e32 v141, v143, v179
	v_sub_f32_e32 v140, v142, v178
	v_sub_f32_e32 v139, v171, v175
	v_sub_f32_e32 v138, v170, v174
	s_or_b64 exec, exec, s[10:11]

.LBB0_186:
	v_mov_b64_e32 v[108:109], s[76:77]
	s_or_b32 s37, s22, 0x80
	v_mad_i64_i32 v[108:109], s[70:71], v128, s92, v[108:109]
	s_cmp_lt_i32 s37, s89
	s_cselect_b64 s[70:71], -1, 0
	v_cvt_pk_bf16_f32 v118, v120, v121
	v_cvt_pk_bf16_f32 v119, v122, v123
	v_cvt_pk_bf16_f32 v120, v124, v125
	v_cvt_pk_bf16_f32 v121, v126, v127
	v_lshl_add_u64 v[108:109], v[164:165], 1, v[108:109]
	s_and_b64 s[70:71], s[30:31], s[70:71]
	global_store_dwordx4 v[108:109], v[118:121], off
	v_pk_mul_f32 v[124:125], v[98:99], v[104:105]
	s_andn2_b64 vcc, exec, s[70:71]
	v_pk_mul_f32 v[120:121], v[102:103], v[104:105]
	v_pk_mul_f32 v[118:119], v[100:101], v[130:131]
	v_pk_mul_f32 v[122:123], v[96:97], v[130:131]
	s_cbranch_vccnz .LBB0_194
	v_and_b32_e32 v105, 64, v195
	v_xor_b32_e32 v104, 16, v195
	v_add_u32_e32 v105, 64, v105
	v_cmp_lt_i32_e32 vcc, v104, v105
	s_nop 1
	v_cndmask_b32_e32 v104, v195, v104, vcc
	v_lshlrev_b32_e32 v104, 2, v104
	s_waitcnt lgkmcnt(0)
	s_and_saveexec_b64 s[98:99], s[0:1]
	v_lshlrev_b32_e32 v240, 2, v129
	global_load_dwordx4 v[166:169], v240, s[64:65]
	global_load_dwordx4 v[170:173], v240, s[44:45]
	global_load_dwordx4 v[174:177], v240, s[64:65] offset:16
	global_load_dwordx4 v[198:201], v240, s[44:45] offset:16
	s_mov_b64 exec, s[98:99]
	ds_bpermute_b32 v132, v104, v118
	ds_bpermute_b32 v136, v104, v122
	ds_bpermute_b32 v133, v104, v119
	ds_bpermute_b32 v137, v104, v123
	ds_bpermute_b32 v126, v104, v120
	ds_bpermute_b32 v140, v104, v124
	ds_bpermute_b32 v127, v104, v121
	ds_bpermute_b32 v141, v104, v125
	s_and_saveexec_b64 s[70:71], s[0:1]
	s_cbranch_execz .LBB0_193
	s_waitcnt vmcnt(0)
	v_pk_mul_f32 v[104:105], v[120:121], v[168:169]
	v_pk_mul_f32 v[114:115], v[118:119], v[166:167]
	s_waitcnt lgkmcnt(5)
	v_pk_mul_f32 v[134:135], v[170:171], v[132:133]
	s_waitcnt lgkmcnt(1)
	v_pk_mul_f32 v[138:139], v[172:173], v[126:127]
	v_pk_mul_f32 v[126:127], v[124:125], v[176:177]
	v_pk_mul_f32 v[132:133], v[122:123], v[174:175]
	v_pk_mul_f32 v[136:137], v[198:199], v[136:137]
	s_waitcnt lgkmcnt(0)
	v_pk_mul_f32 v[140:141], v[200:201], v[140:141]
	s_and_saveexec_b64 s[78:79], s[4:5]
	s_xor_b64 s[78:79], exec, s[78:79]
	v_pk_add_f32 v[120:121], v[104:105], v[138:139]
	v_pk_add_f32 v[118:119], v[114:115], v[134:135]
	v_pk_add_f32 v[124:125], v[126:127], v[140:141]
	v_pk_add_f32 v[122:123], v[132:133], v[136:137]
	s_andn2_saveexec_b64 s[78:79], s[78:79]
	v_sub_f32_e32 v121, v105, v139
	v_sub_f32_e32 v120, v104, v138
	v_sub_f32_e32 v119, v115, v135
	v_sub_f32_e32 v118, v114, v134
	v_sub_f32_e32 v125, v127, v141
	v_sub_f32_e32 v124, v126, v140
	v_sub_f32_e32 v123, v133, v137
	v_sub_f32_e32 v122, v132, v136
	s_or_b64 exec, exec, s[78:79]

.LBB0_207:
	v_mov_b64_e32 v[92:93], s[76:77]
	s_or_b32 s37, s22, 0x80
	v_mad_i64_i32 v[92:93], s[70:71], v112, s92, v[92:93]
	s_cmp_lt_i32 s37, s89
	s_cselect_b64 s[70:71], -1, 0
	v_cvt_pk_bf16_f32 v102, v104, v105
	v_cvt_pk_bf16_f32 v103, v106, v107
	v_cvt_pk_bf16_f32 v104, v108, v109
	v_cvt_pk_bf16_f32 v105, v110, v111
	v_lshl_add_u64 v[92:93], v[164:165], 1, v[92:93]
	s_and_b64 s[70:71], s[30:31], s[70:71]
	global_store_dwordx4 v[92:93], v[102:105], off
	v_pk_mul_f32 v[108:109], v[82:83], v[88:89]
	s_andn2_b64 vcc, exec, s[70:71]
	v_pk_mul_f32 v[104:105], v[86:87], v[88:89]
	v_pk_mul_f32 v[102:103], v[84:85], v[114:115]
	v_pk_mul_f32 v[106:107], v[80:81], v[114:115]
	s_cbranch_vccnz .LBB0_215
	v_and_b32_e32 v89, 64, v195
	v_xor_b32_e32 v88, 16, v195
	v_add_u32_e32 v89, 64, v89
	v_cmp_lt_i32_e32 vcc, v88, v89
	s_nop 1
	v_cndmask_b32_e32 v88, v195, v88, vcc
	v_lshlrev_b32_e32 v88, 2, v88
	s_waitcnt lgkmcnt(0)
	s_and_saveexec_b64 s[98:99], s[0:1]
	v_lshlrev_b32_e32 v240, 2, v113
	global_load_dwordx4 v[126:129], v240, s[64:65]
	global_load_dwordx4 v[130:133], v240, s[44:45]
	global_load_dwordx4 v[134:137], v240, s[64:65] offset:16
	global_load_dwordx4 v[138:141], v240, s[44:45] offset:16
	s_mov_b64 exec, s[98:99]
	ds_bpermute_b32 v116, v88, v102
	ds_bpermute_b32 v120, v88, v106
	ds_bpermute_b32 v117, v88, v103
	ds_bpermute_b32 v121, v88, v107
	ds_bpermute_b32 v110, v88, v104
	ds_bpermute_b32 v124, v88, v108
	ds_bpermute_b32 v111, v88, v105
	ds_bpermute_b32 v125, v88, v109
	s_and_saveexec_b64 s[70:71], s[0:1]
	s_cbranch_execz .LBB0_214
	s_waitcnt vmcnt(0)
	v_pk_mul_f32 v[88:89], v[104:105], v[128:129]
	v_pk_mul_f32 v[98:99], v[102:103], v[126:127]
	s_waitcnt lgkmcnt(5)
	v_pk_mul_f32 v[118:119], v[130:131], v[116:117]
	s_waitcnt lgkmcnt(1)
	v_pk_mul_f32 v[122:123], v[132:133], v[110:111]
	v_pk_mul_f32 v[110:111], v[108:109], v[136:137]
	v_pk_mul_f32 v[116:117], v[106:107], v[134:135]
	v_pk_mul_f32 v[120:121], v[138:139], v[120:121]
	s_waitcnt lgkmcnt(0)
	v_pk_mul_f32 v[124:125], v[140:141], v[124:125]
	s_and_saveexec_b64 s[78:79], s[4:5]
	s_xor_b64 s[78:79], exec, s[78:79]
	v_pk_add_f32 v[104:105], v[88:89], v[122:123]
	v_pk_add_f32 v[102:103], v[98:99], v[118:119]
	v_pk_add_f32 v[108:109], v[110:111], v[124:125]
	v_pk_add_f32 v[106:107], v[116:117], v[120:121]
	s_andn2_saveexec_b64 s[78:79], s[78:79]
	v_sub_f32_e32 v105, v89, v123
	v_sub_f32_e32 v104, v88, v122
	v_sub_f32_e32 v103, v99, v119
	v_sub_f32_e32 v102, v98, v118
	v_sub_f32_e32 v109, v111, v125
	v_sub_f32_e32 v108, v110, v124
	v_sub_f32_e32 v107, v117, v121
	v_sub_f32_e32 v106, v116, v120
	s_or_b64 exec, exec, s[78:79]

.LBB0_228:
	v_mov_b64_e32 v[76:77], s[76:77]
	s_or_b32 s37, s22, 0x80
	v_mad_i64_i32 v[76:77], s[70:71], v96, s92, v[76:77]
	s_cmp_lt_i32 s37, s89
	s_cselect_b64 s[70:71], -1, 0
	v_cvt_pk_bf16_f32 v86, v88, v89
	v_cvt_pk_bf16_f32 v87, v90, v91
	v_cvt_pk_bf16_f32 v88, v92, v93
	v_cvt_pk_bf16_f32 v89, v94, v95
	v_lshl_add_u64 v[76:77], v[164:165], 1, v[76:77]
	s_and_b64 s[70:71], s[30:31], s[70:71]
	global_store_dwordx4 v[76:77], v[86:89], off
	v_pk_mul_f32 v[92:93], v[66:67], v[72:73]
	s_andn2_b64 vcc, exec, s[70:71]
	v_pk_mul_f32 v[88:89], v[70:71], v[72:73]
	v_pk_mul_f32 v[86:87], v[68:69], v[98:99]
	v_pk_mul_f32 v[90:91], v[64:65], v[98:99]
	s_cbranch_vccnz .LBB0_236
	v_and_b32_e32 v73, 64, v195
	v_xor_b32_e32 v72, 16, v195
	v_add_u32_e32 v73, 64, v73
	v_cmp_lt_i32_e32 vcc, v72, v73
	s_nop 1
	v_cndmask_b32_e32 v72, v195, v72, vcc
	v_lshlrev_b32_e32 v72, 2, v72
	s_waitcnt lgkmcnt(0)
	s_and_saveexec_b64 s[98:99], s[0:1]
	v_lshlrev_b32_e32 v240, 2, v97
	global_load_dwordx4 v[110:113], v240, s[64:65]
	global_load_dwordx4 v[114:117], v240, s[44:45]
	global_load_dwordx4 v[118:121], v240, s[64:65] offset:16
	global_load_dwordx4 v[122:125], v240, s[44:45] offset:16
	s_mov_b64 exec, s[98:99]
	ds_bpermute_b32 v100, v72, v86
	ds_bpermute_b32 v104, v72, v90
	ds_bpermute_b32 v101, v72, v87
	ds_bpermute_b32 v105, v72, v91
	ds_bpermute_b32 v94, v72, v88
	ds_bpermute_b32 v108, v72, v92
	ds_bpermute_b32 v95, v72, v89
	ds_bpermute_b32 v109, v72, v93
	s_and_saveexec_b64 s[70:71], s[0:1]
	s_cbranch_execz .LBB0_235
	s_waitcnt vmcnt(0)
	v_pk_mul_f32 v[72:73], v[88:89], v[112:113]
	v_pk_mul_f32 v[82:83], v[86:87], v[110:111]
	s_waitcnt lgkmcnt(5)
	v_pk_mul_f32 v[102:103], v[114:115], v[100:101]
	s_waitcnt lgkmcnt(1)
	v_pk_mul_f32 v[106:107], v[116:117], v[94:95]
	v_pk_mul_f32 v[94:95], v[92:93], v[120:121]
	v_pk_mul_f32 v[100:101], v[90:91], v[118:119]
	v_pk_mul_f32 v[104:105], v[122:123], v[104:105]
	s_waitcnt lgkmcnt(0)
	v_pk_mul_f32 v[108:109], v[124:125], v[108:109]
	s_and_saveexec_b64 s[78:79], s[4:5]
	s_xor_b64 s[78:79], exec, s[78:79]
	v_pk_add_f32 v[88:89], v[72:73], v[106:107]
	v_pk_add_f32 v[86:87], v[82:83], v[102:103]
	v_pk_add_f32 v[92:93], v[94:95], v[108:109]
	v_pk_add_f32 v[90:91], v[100:101], v[104:105]
	s_andn2_saveexec_b64 s[78:79], s[78:79]
	v_sub_f32_e32 v89, v73, v107
	v_sub_f32_e32 v88, v72, v106
	v_sub_f32_e32 v87, v83, v103
	v_sub_f32_e32 v86, v82, v102
	v_sub_f32_e32 v93, v95, v109
	v_sub_f32_e32 v92, v94, v108
	v_sub_f32_e32 v91, v101, v105
	v_sub_f32_e32 v90, v100, v104
	s_or_b64 exec, exec, s[78:79]

.LBB0_249:
	v_mov_b64_e32 v[60:61], s[76:77]
	s_or_b32 s37, s22, 0x80
	v_mad_i64_i32 v[60:61], s[70:71], v80, s92, v[60:61]
	s_cmp_lt_i32 s37, s89
	s_cselect_b64 s[70:71], -1, 0
	v_cvt_pk_bf16_f32 v70, v72, v73
	v_cvt_pk_bf16_f32 v71, v74, v75
	v_cvt_pk_bf16_f32 v72, v76, v77
	v_cvt_pk_bf16_f32 v73, v78, v79
	v_lshl_add_u64 v[60:61], v[164:165], 1, v[60:61]
	s_and_b64 s[70:71], s[30:31], s[70:71]
	global_store_dwordx4 v[60:61], v[70:73], off
	v_pk_mul_f32 v[76:77], v[50:51], v[56:57]
	s_andn2_b64 vcc, exec, s[70:71]
	v_pk_mul_f32 v[72:73], v[54:55], v[56:57]
	v_pk_mul_f32 v[70:71], v[52:53], v[82:83]
	v_pk_mul_f32 v[74:75], v[48:49], v[82:83]
	s_cbranch_vccnz .LBB0_257
	v_and_b32_e32 v57, 64, v195
	v_xor_b32_e32 v56, 16, v195
	v_add_u32_e32 v57, 64, v57
	v_cmp_lt_i32_e32 vcc, v56, v57
	s_nop 1
	v_cndmask_b32_e32 v56, v195, v56, vcc
	v_lshlrev_b32_e32 v56, 2, v56
	s_waitcnt lgkmcnt(0)
	s_and_saveexec_b64 s[98:99], s[0:1]
	v_lshlrev_b32_e32 v240, 2, v81
	global_load_dwordx4 v[94:97], v240, s[64:65]
	global_load_dwordx4 v[98:101], v240, s[44:45]
	global_load_dwordx4 v[102:105], v240, s[64:65] offset:16
	global_load_dwordx4 v[106:109], v240, s[44:45] offset:16
	s_mov_b64 exec, s[98:99]
	ds_bpermute_b32 v84, v56, v70
	ds_bpermute_b32 v88, v56, v74
	ds_bpermute_b32 v85, v56, v71
	ds_bpermute_b32 v89, v56, v75
	ds_bpermute_b32 v78, v56, v72
	ds_bpermute_b32 v92, v56, v76
	ds_bpermute_b32 v79, v56, v73
	ds_bpermute_b32 v93, v56, v77
	s_and_saveexec_b64 s[70:71], s[0:1]
	s_cbranch_execz .LBB0_256
	s_waitcnt vmcnt(0)
	v_pk_mul_f32 v[56:57], v[72:73], v[96:97]
	v_pk_mul_f32 v[66:67], v[70:71], v[94:95]
	s_waitcnt lgkmcnt(5)
	v_pk_mul_f32 v[86:87], v[98:99], v[84:85]
	s_waitcnt lgkmcnt(1)
	v_pk_mul_f32 v[90:91], v[100:101], v[78:79]
	v_pk_mul_f32 v[78:79], v[76:77], v[104:105]
	v_pk_mul_f32 v[84:85], v[74:75], v[102:103]
	v_pk_mul_f32 v[88:89], v[106:107], v[88:89]
	s_waitcnt lgkmcnt(0)
	v_pk_mul_f32 v[92:93], v[108:109], v[92:93]
	s_and_saveexec_b64 s[78:79], s[4:5]
	s_xor_b64 s[78:79], exec, s[78:79]
	v_pk_add_f32 v[72:73], v[56:57], v[90:91]
	v_pk_add_f32 v[70:71], v[66:67], v[86:87]
	v_pk_add_f32 v[76:77], v[78:79], v[92:93]
	v_pk_add_f32 v[74:75], v[84:85], v[88:89]
	s_andn2_saveexec_b64 s[78:79], s[78:79]
	v_sub_f32_e32 v73, v57, v91
	v_sub_f32_e32 v72, v56, v90
	v_sub_f32_e32 v71, v67, v87
	v_sub_f32_e32 v70, v66, v86
	v_sub_f32_e32 v77, v79, v93
	v_sub_f32_e32 v76, v78, v92
	v_sub_f32_e32 v75, v85, v89
	v_sub_f32_e32 v74, v84, v88
	s_or_b64 exec, exec, s[78:79]

.LBB0_270:
	v_mov_b64_e32 v[44:45], s[76:77]
	s_or_b32 s37, s22, 0x80
	v_mad_i64_i32 v[44:45], s[70:71], v64, s92, v[44:45]
	s_cmp_lt_i32 s37, s89
	s_cselect_b64 s[70:71], -1, 0
	v_cvt_pk_bf16_f32 v54, v56, v57
	v_cvt_pk_bf16_f32 v55, v58, v59
	v_cvt_pk_bf16_f32 v56, v60, v61
	v_cvt_pk_bf16_f32 v57, v62, v63
	v_lshl_add_u64 v[44:45], v[164:165], 1, v[44:45]
	s_and_b64 s[70:71], s[30:31], s[70:71]
	global_store_dwordx4 v[44:45], v[54:57], off
	v_pk_mul_f32 v[60:61], v[34:35], v[40:41]
	s_andn2_b64 vcc, exec, s[70:71]
	v_pk_mul_f32 v[56:57], v[38:39], v[40:41]
	v_pk_mul_f32 v[54:55], v[36:37], v[66:67]
	v_pk_mul_f32 v[58:59], v[32:33], v[66:67]
	s_cbranch_vccnz .LBB0_278
	v_and_b32_e32 v41, 64, v195
	v_xor_b32_e32 v40, 16, v195
	v_add_u32_e32 v41, 64, v41
	v_cmp_lt_i32_e32 vcc, v40, v41
	s_nop 1
	v_cndmask_b32_e32 v40, v195, v40, vcc
	v_lshlrev_b32_e32 v40, 2, v40
	s_waitcnt lgkmcnt(0)
	s_and_saveexec_b64 s[98:99], s[0:1]
	v_lshlrev_b32_e32 v240, 2, v65
	global_load_dwordx4 v[78:81], v240, s[64:65]
	global_load_dwordx4 v[82:85], v240, s[44:45]
	global_load_dwordx4 v[86:89], v240, s[64:65] offset:16
	global_load_dwordx4 v[90:93], v240, s[44:45] offset:16
	s_mov_b64 exec, s[98:99]
	ds_bpermute_b32 v68, v40, v54
	ds_bpermute_b32 v72, v40, v58
	ds_bpermute_b32 v69, v40, v55
	ds_bpermute_b32 v73, v40, v59
	ds_bpermute_b32 v62, v40, v56
	ds_bpermute_b32 v76, v40, v60
	ds_bpermute_b32 v63, v40, v57
	ds_bpermute_b32 v77, v40, v61
	s_and_saveexec_b64 s[70:71], s[0:1]
	s_cbranch_execz .LBB0_277
	s_waitcnt vmcnt(0)
	v_pk_mul_f32 v[40:41], v[56:57], v[80:81]
	v_pk_mul_f32 v[50:51], v[54:55], v[78:79]
	s_waitcnt lgkmcnt(5)
	v_pk_mul_f32 v[70:71], v[82:83], v[68:69]
	s_waitcnt lgkmcnt(1)
	v_pk_mul_f32 v[74:75], v[84:85], v[62:63]
	v_pk_mul_f32 v[62:63], v[60:61], v[88:89]
	v_pk_mul_f32 v[68:69], v[58:59], v[86:87]
	v_pk_mul_f32 v[72:73], v[90:91], v[72:73]
	s_waitcnt lgkmcnt(0)
	v_pk_mul_f32 v[76:77], v[92:93], v[76:77]
	s_and_saveexec_b64 s[78:79], s[4:5]
	s_xor_b64 s[78:79], exec, s[78:79]
	v_pk_add_f32 v[56:57], v[40:41], v[74:75]
	v_pk_add_f32 v[54:55], v[50:51], v[70:71]
	v_pk_add_f32 v[60:61], v[62:63], v[76:77]
	v_pk_add_f32 v[58:59], v[68:69], v[72:73]
	s_andn2_saveexec_b64 s[78:79], s[78:79]
	v_sub_f32_e32 v57, v41, v75
	v_sub_f32_e32 v56, v40, v74
	v_sub_f32_e32 v55, v51, v71
	v_sub_f32_e32 v54, v50, v70
	v_sub_f32_e32 v61, v63, v77
	v_sub_f32_e32 v60, v62, v76
	v_sub_f32_e32 v59, v69, v73
	v_sub_f32_e32 v58, v68, v72
	s_or_b64 exec, exec, s[78:79]

.LBB0_291:
	v_mov_b64_e32 v[28:29], s[76:77]
	s_or_b32 s37, s22, 0x80
	v_mad_i64_i32 v[28:29], s[70:71], v48, s92, v[28:29]
	s_cmp_lt_i32 s37, s89
	s_cselect_b64 s[70:71], -1, 0
	v_cvt_pk_bf16_f32 v38, v40, v41
	v_cvt_pk_bf16_f32 v39, v42, v43
	v_cvt_pk_bf16_f32 v40, v44, v45
	v_cvt_pk_bf16_f32 v41, v46, v47
	v_lshl_add_u64 v[28:29], v[164:165], 1, v[28:29]
	s_and_b64 s[70:71], s[30:31], s[70:71]
	global_store_dwordx4 v[28:29], v[38:41], off
	v_pk_mul_f32 v[44:45], v[18:19], v[24:25]
	s_andn2_b64 vcc, exec, s[70:71]
	v_pk_mul_f32 v[40:41], v[22:23], v[24:25]
	v_pk_mul_f32 v[38:39], v[20:21], v[50:51]
	v_pk_mul_f32 v[42:43], v[16:17], v[50:51]
	s_cbranch_vccnz .LBB0_299
	v_and_b32_e32 v25, 64, v195
	v_xor_b32_e32 v24, 16, v195
	v_add_u32_e32 v25, 64, v25
	v_cmp_lt_i32_e32 vcc, v24, v25
	s_nop 1
	v_cndmask_b32_e32 v24, v195, v24, vcc
	v_lshlrev_b32_e32 v24, 2, v24
	s_waitcnt lgkmcnt(0)
	s_and_saveexec_b64 s[98:99], s[0:1]
	v_lshlrev_b32_e32 v240, 2, v49
	global_load_dwordx4 v[62:65], v240, s[64:65]
	global_load_dwordx4 v[66:69], v240, s[44:45]
	global_load_dwordx4 v[70:73], v240, s[64:65] offset:16
	global_load_dwordx4 v[74:77], v240, s[44:45] offset:16
	s_mov_b64 exec, s[98:99]
	ds_bpermute_b32 v52, v24, v38
	ds_bpermute_b32 v56, v24, v42
	ds_bpermute_b32 v53, v24, v39
	ds_bpermute_b32 v57, v24, v43
	ds_bpermute_b32 v46, v24, v40
	ds_bpermute_b32 v60, v24, v44
	ds_bpermute_b32 v47, v24, v41
	ds_bpermute_b32 v61, v24, v45
	s_and_saveexec_b64 s[70:71], s[0:1]
	s_cbranch_execz .LBB0_298
	s_waitcnt vmcnt(0)
	v_pk_mul_f32 v[24:25], v[40:41], v[64:65]
	v_pk_mul_f32 v[34:35], v[38:39], v[62:63]
	s_waitcnt lgkmcnt(5)
	v_pk_mul_f32 v[54:55], v[66:67], v[52:53]
	s_waitcnt lgkmcnt(1)
	v_pk_mul_f32 v[58:59], v[68:69], v[46:47]
	v_pk_mul_f32 v[46:47], v[44:45], v[72:73]
	v_pk_mul_f32 v[52:53], v[42:43], v[70:71]
	v_pk_mul_f32 v[56:57], v[74:75], v[56:57]
	s_waitcnt lgkmcnt(0)
	v_pk_mul_f32 v[60:61], v[76:77], v[60:61]
	s_and_saveexec_b64 s[78:79], s[4:5]
	s_xor_b64 s[78:79], exec, s[78:79]
	v_pk_add_f32 v[40:41], v[24:25], v[58:59]
	v_pk_add_f32 v[38:39], v[34:35], v[54:55]
	v_pk_add_f32 v[44:45], v[46:47], v[60:61]
	v_pk_add_f32 v[42:43], v[52:53], v[56:57]
	s_andn2_saveexec_b64 s[78:79], s[78:79]
	v_sub_f32_e32 v41, v25, v59
	v_sub_f32_e32 v40, v24, v58
	v_sub_f32_e32 v39, v35, v55
	v_sub_f32_e32 v38, v34, v54
	v_sub_f32_e32 v45, v47, v61
	v_sub_f32_e32 v44, v46, v60
	v_sub_f32_e32 v43, v53, v57
	v_sub_f32_e32 v42, v52, v56
	s_or_b64 exec, exec, s[78:79]

.LBB0_314:
	v_mov_b64_e32 v[12:13], s[76:77]
	v_mad_i64_i32 v[12:13], s[8:9], v32, s92, v[12:13]
	s_or_b32 s8, s22, 0x80
	s_cmp_lt_i32 s8, s89
	s_cselect_b64 s[8:9], -1, 0
	v_cvt_pk_bf16_f32 v22, v24, v25
	v_cvt_pk_bf16_f32 v23, v26, v27
	v_cvt_pk_bf16_f32 v24, v28, v29
	v_cvt_pk_bf16_f32 v25, v30, v31
	v_lshl_add_u64 v[12:13], v[164:165], 1, v[12:13]
	s_and_b64 s[8:9], s[30:31], s[8:9]
	global_store_dwordx4 v[12:13], v[22:25], off
	v_pk_mul_f32 v[28:29], v[2:3], v[8:9]
	s_andn2_b64 vcc, exec, s[8:9]
	v_pk_mul_f32 v[24:25], v[6:7], v[8:9]
	v_pk_mul_f32 v[22:23], v[4:5], v[34:35]
	v_pk_mul_f32 v[26:27], v[0:1], v[34:35]
	s_cbranch_vccnz .LBB0_322
	v_and_b32_e32 v9, 64, v195
	v_xor_b32_e32 v8, 16, v195
	v_add_u32_e32 v9, 64, v9
	v_cmp_lt_i32_e32 vcc, v8, v9
	s_nop 1
	v_cndmask_b32_e32 v8, v195, v8, vcc
	v_lshlrev_b32_e32 v8, 2, v8
	s_waitcnt lgkmcnt(0)
	s_and_saveexec_b64 s[98:99], s[0:1]
	v_lshlrev_b32_e32 v240, 2, v33
	global_load_dwordx4 v[46:49], v240, s[64:65]
	global_load_dwordx4 v[50:53], v240, s[44:45]
	global_load_dwordx4 v[54:57], v240, s[64:65] offset:16
	global_load_dwordx4 v[58:61], v240, s[44:45] offset:16
	s_mov_b64 exec, s[98:99]
	ds_bpermute_b32 v36, v8, v22
	ds_bpermute_b32 v40, v8, v26
	ds_bpermute_b32 v37, v8, v23
	ds_bpermute_b32 v41, v8, v27
	ds_bpermute_b32 v30, v8, v24
	ds_bpermute_b32 v44, v8, v28
	ds_bpermute_b32 v31, v8, v25
	ds_bpermute_b32 v45, v8, v29
	s_and_saveexec_b64 s[8:9], s[0:1]
	s_cbranch_execz .LBB0_321
	s_waitcnt vmcnt(0)
	v_pk_mul_f32 v[8:9], v[24:25], v[48:49]
	v_pk_mul_f32 v[18:19], v[22:23], v[46:47]
	s_waitcnt lgkmcnt(5)
	v_pk_mul_f32 v[38:39], v[50:51], v[36:37]
	s_waitcnt lgkmcnt(1)
	v_pk_mul_f32 v[42:43], v[52:53], v[30:31]
	v_pk_mul_f32 v[30:31], v[28:29], v[56:57]
	v_pk_mul_f32 v[36:37], v[26:27], v[54:55]
	v_pk_mul_f32 v[40:41], v[58:59], v[40:41]
	s_waitcnt lgkmcnt(0)
	v_pk_mul_f32 v[44:45], v[60:61], v[44:45]
	s_and_saveexec_b64 s[10:11], s[4:5]
	s_xor_b64 s[10:11], exec, s[10:11]
	v_pk_add_f32 v[24:25], v[8:9], v[42:43]
	v_pk_add_f32 v[22:23], v[18:19], v[38:39]
	v_pk_add_f32 v[28:29], v[30:31], v[44:45]
	v_pk_add_f32 v[26:27], v[36:37], v[40:41]
	s_andn2_saveexec_b64 s[10:11], s[10:11]
	v_sub_f32_e32 v25, v9, v43
	v_sub_f32_e32 v24, v8, v42
	v_sub_f32_e32 v23, v19, v39
	v_sub_f32_e32 v22, v18, v38
	v_sub_f32_e32 v29, v31, v45
	v_sub_f32_e32 v28, v30, v44
	v_sub_f32_e32 v27, v37, v41
	v_sub_f32_e32 v26, v36, v40
	s_or_b64 exec, exec, s[10:11]

.LBB0_880:
	s_lshl_b32 s21, s8, 8
	s_lshl_b32 s8, s9, 10
	v_add_u32_e32 v177, s8, v172
	ds_read_b32 v146, v177
	s_cmp_lt_i32 s10, 4
	s_cselect_b64 s[8:9], -1, 0
	v_add_u32_e32 v179, s21, v162
	v_lshlrev_b32_e32 v144, 3, v179
	s_and_b64 s[28:29], s[18:19], s[8:9]
	v_and_b32_e32 v178, 0xfe78, v144
	v_cndmask_b32_e64 v144, 0, 1, s[28:29]
	s_waitcnt lgkmcnt(0)
	v_pk_mul_f32 v[126:127], v[126:127], v[146:147] op_sel_hi:[1,0]
	v_pk_mul_f32 v[124:125], v[124:125], v[146:147] op_sel_hi:[1,0]
	v_pk_mul_f32 v[122:123], v[122:123], v[146:147] op_sel_hi:[1,0]
	v_cmp_ne_u32_e64 s[8:9], 1, v144
	s_andn2_b64 vcc, exec, s[28:29]
	v_pk_mul_f32 v[120:121], v[120:121], v[146:147] op_sel_hi:[1,0]
	s_cbranch_vccnz .LBB0_888
	v_and_b32_e32 v145, 64, v176
	v_xor_b32_e32 v144, 16, v176
	v_add_u32_e32 v145, 64, v145
	v_cmp_lt_i32_e32 vcc, v144, v145
	s_nop 1
	v_cndmask_b32_e32 v144, v176, v144, vcc
	v_lshlrev_b32_e32 v144, 2, v144
	s_and_saveexec_b64 s[98:99], s[0:1]
	v_lshlrev_b32_e32 v240, 2, v178
	global_load_dwordx4 v[184:187], v240, s[64:65]
	global_load_dwordx4 v[188:191], v240, s[44:45]
	global_load_dwordx4 v[192:195], v240, s[64:65] offset:16
	global_load_dwordx4 v[196:199], v240, s[44:45] offset:16
	s_mov_b64 exec, s[98:99]
	ds_bpermute_b32 v152, v144, v124
	ds_bpermute_b32 v156, v144, v120
	ds_bpermute_b32 v153, v144, v125
	ds_bpermute_b32 v157, v144, v121
	ds_bpermute_b32 v150, v144, v126
	ds_bpermute_b32 v160, v144, v122
	ds_bpermute_b32 v151, v144, v127
	ds_bpermute_b32 v161, v144, v123
	s_and_saveexec_b64 s[28:29], s[0:1]
	s_cbranch_execz .LBB0_887
	s_waitcnt vmcnt(0)
	v_pk_mul_f32 v[144:145], v[126:127], v[186:187]
	v_pk_mul_f32 v[148:149], v[124:125], v[184:185]
	s_waitcnt lgkmcnt(5)
	v_pk_mul_f32 v[154:155], v[188:189], v[152:153]
	s_waitcnt lgkmcnt(1)
	v_pk_mul_f32 v[158:159], v[190:191], v[150:151]
	v_pk_mul_f32 v[150:151], v[122:123], v[194:195]
	v_pk_mul_f32 v[152:153], v[120:121], v[192:193]
	v_pk_mul_f32 v[156:157], v[196:197], v[156:157]
	s_waitcnt lgkmcnt(0)
	v_pk_mul_f32 v[160:161], v[198:199], v[160:161]
	s_and_saveexec_b64 s[30:31], s[4:5]
	s_xor_b64 s[30:31], exec, s[30:31]
	v_pk_add_f32 v[126:127], v[144:145], v[158:159]
	v_pk_add_f32 v[124:125], v[148:149], v[154:155]
	v_pk_add_f32 v[122:123], v[150:151], v[160:161]
	v_pk_add_f32 v[120:121], v[152:153], v[156:157]
	s_andn2_saveexec_b64 s[30:31], s[30:31]
	v_sub_f32_e32 v127, v145, v159
	v_sub_f32_e32 v126, v144, v158
	v_sub_f32_e32 v125, v149, v155
	v_sub_f32_e32 v124, v148, v154
	v_sub_f32_e32 v123, v151, v161
	v_sub_f32_e32 v122, v150, v160
	v_sub_f32_e32 v121, v153, v157
	v_sub_f32_e32 v120, v152, v156
	s_or_b64 exec, exec, s[30:31]

.LBB0_890:
	v_lshl_or_b32 v144, s10, 8, v164
	v_cvt_pk_bf16_f32 v124, v124, v125
	v_cvt_pk_bf16_f32 v125, v126, v127
	v_cvt_pk_bf16_f32 v126, v120, v121
	v_mov_b64_e32 v[120:121], s[76:77]
	v_mov_b32_e32 v147, v146
	v_ashrrev_i32_e32 v145, 31, v144
	v_cvt_pk_bf16_f32 v127, v122, v123
	v_mad_i64_i32 v[120:121], s[10:11], v179, s51, v[120:121]
	v_mov_b32_e32 v122, v146
	v_mov_b32_e32 v123, v146
	v_lshl_add_u64 v[120:121], v[144:145], 1, v[120:121]
	v_pk_mul_f32 v[118:119], v[118:119], v[122:123]
	v_pk_mul_f32 v[116:117], v[116:117], v[146:147]
	v_pk_mul_f32 v[114:115], v[114:115], v[122:123]
	s_and_b64 vcc, exec, s[8:9]
	v_pk_mul_f32 v[112:113], v[112:113], v[146:147]
	global_store_dwordx4 v[120:121], v[124:127], off
	s_cbranch_vccnz .LBB0_898
	v_and_b32_e32 v123, 64, v176
	v_xor_b32_e32 v122, 16, v176
	v_add_u32_e32 v123, 64, v123
	v_cmp_lt_i32_e32 vcc, v122, v123
	s_nop 1
	v_cndmask_b32_e32 v122, v176, v122, vcc
	v_lshlrev_b32_e32 v122, 2, v122
	s_and_saveexec_b64 s[98:99], s[0:1]
	v_lshlrev_b32_e32 v240, 2, v178
	global_load_dwordx4 v[156:159], v240, s[64:65]
	global_load_dwordx4 v[184:187], v240, s[44:45]
	global_load_dwordx4 v[188:191], v240, s[64:65] offset:16
	global_load_dwordx4 v[192:195], v240, s[44:45] offset:16
	s_mov_b64 exec, s[98:99]
	ds_bpermute_b32 v146, v122, v116
	s_waitcnt lgkmcnt(0)
	ds_bpermute_b32 v150, v122, v112
	ds_bpermute_b32 v147, v122, v117
	ds_bpermute_b32 v151, v122, v113
	ds_bpermute_b32 v126, v122, v118
	ds_bpermute_b32 v154, v122, v114
	ds_bpermute_b32 v127, v122, v119
	ds_bpermute_b32 v155, v122, v115
	s_and_saveexec_b64 s[10:11], s[0:1]
	s_cbranch_execz .LBB0_897
	s_waitcnt vmcnt(0)
	v_pk_mul_f32 v[122:123], v[118:119], v[158:159]
	v_pk_mul_f32 v[124:125], v[116:117], v[156:157]
	s_waitcnt lgkmcnt(5)
	v_pk_mul_f32 v[148:149], v[184:185], v[146:147]
	s_waitcnt lgkmcnt(1)
	v_pk_mul_f32 v[152:153], v[186:187], v[126:127]
	v_pk_mul_f32 v[126:127], v[114:115], v[190:191]
	v_pk_mul_f32 v[146:147], v[112:113], v[188:189]
	v_pk_mul_f32 v[150:151], v[192:193], v[150:151]
	s_waitcnt lgkmcnt(0)
	v_pk_mul_f32 v[154:155], v[194:195], v[154:155]
	s_and_saveexec_b64 s[30:31], s[4:5]
	s_xor_b64 s[30:31], exec, s[30:31]
	v_pk_add_f32 v[118:119], v[122:123], v[152:153]
	v_pk_add_f32 v[116:117], v[124:125], v[148:149]
	v_pk_add_f32 v[114:115], v[126:127], v[154:155]
	v_pk_add_f32 v[112:113], v[146:147], v[150:151]
	s_andn2_saveexec_b64 s[30:31], s[30:31]
	v_sub_f32_e32 v119, v123, v153
	v_sub_f32_e32 v118, v122, v152
	v_sub_f32_e32 v117, v125, v149
	v_sub_f32_e32 v116, v124, v148
	v_sub_f32_e32 v115, v127, v155
	v_sub_f32_e32 v114, v126, v154
	v_sub_f32_e32 v113, v147, v151
	v_sub_f32_e32 v112, v146, v150
	s_or_b64 exec, exec, s[30:31]

.LBB0_900:
	v_cvt_pk_bf16_f32 v116, v116, v117
	v_cvt_pk_bf16_f32 v117, v118, v119
	v_cvt_pk_bf16_f32 v118, v112, v113
	ds_read_b32 v112, v177 offset:64
	v_add_u32_e32 v149, s21, v165
	v_lshlrev_b32_e32 v113, 3, v149
	v_cvt_pk_bf16_f32 v119, v114, v115
	v_and_b32_e32 v148, 0xfef8, v113
	s_waitcnt lgkmcnt(0)
	v_pk_mul_f32 v[110:111], v[110:111], v[112:113] op_sel_hi:[1,0]
	v_pk_mul_f32 v[108:109], v[108:109], v[112:113] op_sel_hi:[1,0]
	v_pk_mul_f32 v[106:107], v[106:107], v[112:113] op_sel_hi:[1,0]
	s_and_b64 vcc, exec, s[8:9]
	v_pk_mul_f32 v[104:105], v[104:105], v[112:113] op_sel_hi:[1,0]
	global_store_dwordx4 v[120:121], v[116:119], off offset:256
	s_cbranch_vccnz .LBB0_908
	v_and_b32_e32 v114, 64, v176
	v_xor_b32_e32 v113, 16, v176
	v_add_u32_e32 v114, 64, v114
	v_cmp_lt_i32_e32 vcc, v113, v114
	s_nop 1
	v_cndmask_b32_e32 v113, v176, v113, vcc
	v_lshlrev_b32_e32 v113, 2, v113
	s_and_saveexec_b64 s[98:99], s[0:1]
	v_lshlrev_b32_e32 v240, 2, v148
	global_load_dwordx4 v[150:153], v240, s[64:65]
	global_load_dwordx4 v[154:157], v240, s[44:45]
	global_load_dwordx4 v[158:161], v240, s[64:65] offset:16
	global_load_dwordx4 v[184:187], v240, s[44:45] offset:16
	s_mov_b64 exec, s[98:99]
	ds_bpermute_b32 v120, v113, v108
	ds_bpermute_b32 v124, v113, v104
	ds_bpermute_b32 v121, v113, v109
	ds_bpermute_b32 v125, v113, v105
	ds_bpermute_b32 v118, v113, v110
	ds_bpermute_b32 v146, v113, v106
	ds_bpermute_b32 v119, v113, v111
	ds_bpermute_b32 v147, v113, v107
	s_and_saveexec_b64 s[28:29], s[0:1]
	s_cbranch_execz .LBB0_907
	s_waitcnt vmcnt(0)
	v_pk_mul_f32 v[114:115], v[110:111], v[152:153]
	v_pk_mul_f32 v[116:117], v[108:109], v[150:151]
	s_waitcnt lgkmcnt(5)
	v_pk_mul_f32 v[122:123], v[154:155], v[120:121]
	s_waitcnt lgkmcnt(1)
	v_pk_mul_f32 v[126:127], v[156:157], v[118:119]
	v_pk_mul_f32 v[118:119], v[106:107], v[160:161]
	v_pk_mul_f32 v[120:121], v[104:105], v[158:159]
	v_pk_mul_f32 v[124:125], v[184:185], v[124:125]
	s_waitcnt lgkmcnt(0)
	v_pk_mul_f32 v[146:147], v[186:187], v[146:147]
	s_and_saveexec_b64 s[30:31], s[4:5]
	s_xor_b64 s[30:31], exec, s[30:31]
	v_pk_add_f32 v[110:111], v[114:115], v[126:127]
	v_pk_add_f32 v[108:109], v[116:117], v[122:123]
	v_pk_add_f32 v[106:107], v[118:119], v[146:147]
	v_pk_add_f32 v[104:105], v[120:121], v[124:125]
	s_andn2_saveexec_b64 s[30:31], s[30:31]
	v_sub_f32_e32 v111, v115, v127
	v_sub_f32_e32 v110, v114, v126
	v_sub_f32_e32 v109, v117, v123
	v_sub_f32_e32 v108, v116, v122
	v_sub_f32_e32 v107, v119, v147
	v_sub_f32_e32 v106, v118, v146
	v_sub_f32_e32 v105, v121, v125
	v_sub_f32_e32 v104, v120, v124
	s_or_b64 exec, exec, s[30:31]

.LBB0_910:
	v_cvt_pk_bf16_f32 v108, v108, v109
	v_cvt_pk_bf16_f32 v109, v110, v111
	v_cvt_pk_bf16_f32 v110, v104, v105
	v_mov_b64_e32 v[104:105], s[76:77]
	v_mov_b32_e32 v113, v112
	v_cvt_pk_bf16_f32 v111, v106, v107
	v_mad_i64_i32 v[104:105], s[28:29], v149, s51, v[104:105]
	v_mov_b32_e32 v106, v112
	v_mov_b32_e32 v107, v112
	v_lshl_add_u64 v[104:105], v[144:145], 1, v[104:105]
	v_pk_mul_f32 v[102:103], v[102:103], v[106:107]
	v_pk_mul_f32 v[100:101], v[100:101], v[112:113]
	v_pk_mul_f32 v[98:99], v[98:99], v[106:107]
	s_and_b64 vcc, exec, s[8:9]
	v_pk_mul_f32 v[96:97], v[96:97], v[112:113]
	global_store_dwordx4 v[104:105], v[108:111], off
	s_cbranch_vccnz .LBB0_918
	v_and_b32_e32 v107, 64, v176
	v_xor_b32_e32 v106, 16, v176
	v_add_u32_e32 v107, 64, v107
	v_cmp_lt_i32_e32 vcc, v106, v107
	s_nop 1
	v_cndmask_b32_e32 v106, v176, v106, vcc
	v_lshlrev_b32_e32 v106, 2, v106
	s_and_saveexec_b64 s[98:99], s[0:1]
	v_lshlrev_b32_e32 v240, 2, v148
	global_load_dwordx4 v[122:125], v240, s[64:65]
	global_load_dwordx4 v[146:149], v240, s[44:45]
	global_load_dwordx4 v[150:153], v240, s[64:65] offset:16
	global_load_dwordx4 v[154:157], v240, s[44:45] offset:16
	s_mov_b64 exec, s[98:99]
	ds_bpermute_b32 v112, v106, v100
	ds_bpermute_b32 v116, v106, v96
	ds_bpermute_b32 v113, v106, v101
	ds_bpermute_b32 v117, v106, v97
	ds_bpermute_b32 v110, v106, v102
	s_waitcnt lgkmcnt(0)
	ds_bpermute_b32 v120, v106, v98
	ds_bpermute_b32 v111, v106, v103
	ds_bpermute_b32 v121, v106, v99
	s_and_saveexec_b64 s[28:29], s[0:1]
	s_cbranch_execz .LBB0_917
	s_waitcnt vmcnt(0)
	v_pk_mul_f32 v[106:107], v[102:103], v[124:125]
	v_pk_mul_f32 v[108:109], v[100:101], v[122:123]
	v_pk_mul_f32 v[114:115], v[146:147], v[112:113]
	s_waitcnt lgkmcnt(1)
	v_pk_mul_f32 v[118:119], v[148:149], v[110:111]
	v_pk_mul_f32 v[110:111], v[98:99], v[152:153]
	v_pk_mul_f32 v[112:113], v[96:97], v[150:151]
	v_pk_mul_f32 v[116:117], v[154:155], v[116:117]
	s_waitcnt lgkmcnt(0)
	v_pk_mul_f32 v[120:121], v[156:157], v[120:121]
	s_and_saveexec_b64 s[30:31], s[4:5]
	s_xor_b64 s[30:31], exec, s[30:31]
	v_pk_add_f32 v[102:103], v[106:107], v[118:119]
	v_pk_add_f32 v[100:101], v[108:109], v[114:115]
	v_pk_add_f32 v[98:99], v[110:111], v[120:121]
	v_pk_add_f32 v[96:97], v[112:113], v[116:117]
	s_andn2_saveexec_b64 s[30:31], s[30:31]
	v_sub_f32_e32 v103, v107, v119
	v_sub_f32_e32 v102, v106, v118
	v_sub_f32_e32 v101, v109, v115
	v_sub_f32_e32 v100, v108, v114
	v_sub_f32_e32 v99, v111, v121
	v_sub_f32_e32 v98, v110, v120
	v_sub_f32_e32 v97, v113, v117
	v_sub_f32_e32 v96, v112, v116
	s_or_b64 exec, exec, s[30:31]

.LBB0_920:
	v_cvt_pk_bf16_f32 v100, v100, v101
	v_cvt_pk_bf16_f32 v101, v102, v103
	v_cvt_pk_bf16_f32 v102, v96, v97
	ds_read_b32 v96, v177 offset:128
	v_add_u32_e32 v115, s21, v166
	v_lshlrev_b32_e32 v97, 3, v115
	v_cvt_pk_bf16_f32 v103, v98, v99
	v_and_b32_e32 v114, 0xff78, v97
	s_waitcnt lgkmcnt(0)
	v_pk_mul_f32 v[94:95], v[94:95], v[96:97] op_sel_hi:[1,0]
	v_pk_mul_f32 v[92:93], v[92:93], v[96:97] op_sel_hi:[1,0]
	v_pk_mul_f32 v[90:91], v[90:91], v[96:97] op_sel_hi:[1,0]
	s_and_b64 vcc, exec, s[8:9]
	v_pk_mul_f32 v[88:89], v[88:89], v[96:97] op_sel_hi:[1,0]
	global_store_dwordx4 v[104:105], v[100:103], off offset:256
	s_cbranch_vccnz .LBB0_928
	v_and_b32_e32 v98, 64, v176
	v_xor_b32_e32 v97, 16, v176
	v_add_u32_e32 v98, 64, v98
	v_cmp_lt_i32_e32 vcc, v97, v98
	s_nop 1
	v_cndmask_b32_e32 v97, v176, v97, vcc
	v_lshlrev_b32_e32 v97, 2, v97
	s_and_saveexec_b64 s[98:99], s[0:1]
	v_lshlrev_b32_e32 v240, 2, v114
	global_load_dwordx4 v[116:119], v240, s[64:65]
	global_load_dwordx4 v[120:123], v240, s[44:45]
	global_load_dwordx4 v[124:127], v240, s[64:65] offset:16
	global_load_dwordx4 v[146:149], v240, s[44:45] offset:16
	s_mov_b64 exec, s[98:99]
	ds_bpermute_b32 v104, v97, v92
	ds_bpermute_b32 v108, v97, v88
	ds_bpermute_b32 v105, v97, v93
	ds_bpermute_b32 v109, v97, v89
	ds_bpermute_b32 v102, v97, v94
	ds_bpermute_b32 v112, v97, v90
	ds_bpermute_b32 v103, v97, v95
	ds_bpermute_b32 v113, v97, v91
	s_and_saveexec_b64 s[28:29], s[0:1]
	s_cbranch_execz .LBB0_927
	s_waitcnt vmcnt(0)
	v_pk_mul_f32 v[98:99], v[94:95], v[118:119]
	v_pk_mul_f32 v[100:101], v[92:93], v[116:117]
	s_waitcnt lgkmcnt(5)
	v_pk_mul_f32 v[106:107], v[120:121], v[104:105]
	s_waitcnt lgkmcnt(1)
	v_pk_mul_f32 v[110:111], v[122:123], v[102:103]
	v_pk_mul_f32 v[102:103], v[90:91], v[126:127]
	v_pk_mul_f32 v[104:105], v[88:89], v[124:125]
	v_pk_mul_f32 v[108:109], v[146:147], v[108:109]
	s_waitcnt lgkmcnt(0)
	v_pk_mul_f32 v[112:113], v[148:149], v[112:113]
	s_and_saveexec_b64 s[30:31], s[4:5]
	s_xor_b64 s[30:31], exec, s[30:31]
	v_pk_add_f32 v[94:95], v[98:99], v[110:111]
	v_pk_add_f32 v[92:93], v[100:101], v[106:107]
	v_pk_add_f32 v[90:91], v[102:103], v[112:113]
	v_pk_add_f32 v[88:89], v[104:105], v[108:109]
	s_andn2_saveexec_b64 s[30:31], s[30:31]
	v_sub_f32_e32 v95, v99, v111
	v_sub_f32_e32 v94, v98, v110
	v_sub_f32_e32 v93, v101, v107
	v_sub_f32_e32 v92, v100, v106
	v_sub_f32_e32 v91, v103, v113
	v_sub_f32_e32 v90, v102, v112
	v_sub_f32_e32 v89, v105, v109
	v_sub_f32_e32 v88, v104, v108
	s_or_b64 exec, exec, s[30:31]

.LBB0_930:
	v_cvt_pk_bf16_f32 v92, v92, v93
	v_cvt_pk_bf16_f32 v93, v94, v95
	v_cvt_pk_bf16_f32 v94, v88, v89
	v_mov_b64_e32 v[88:89], s[76:77]
	v_mov_b32_e32 v97, v96
	v_cvt_pk_bf16_f32 v95, v90, v91
	v_mad_i64_i32 v[88:89], s[28:29], v115, s51, v[88:89]
	v_mov_b32_e32 v90, v96
	v_mov_b32_e32 v91, v96
	v_lshl_add_u64 v[88:89], v[144:145], 1, v[88:89]
	v_pk_mul_f32 v[86:87], v[86:87], v[90:91]
	v_pk_mul_f32 v[84:85], v[84:85], v[96:97]
	v_pk_mul_f32 v[82:83], v[82:83], v[90:91]
	s_and_b64 vcc, exec, s[8:9]
	v_pk_mul_f32 v[80:81], v[80:81], v[96:97]
	global_store_dwordx4 v[88:89], v[92:95], off
	s_cbranch_vccnz .LBB0_938
	v_and_b32_e32 v91, 64, v176
	v_xor_b32_e32 v90, 16, v176
	v_add_u32_e32 v91, 64, v91
	v_cmp_lt_i32_e32 vcc, v90, v91
	s_nop 1
	v_cndmask_b32_e32 v90, v176, v90, vcc
	v_lshlrev_b32_e32 v90, 2, v90
	s_and_saveexec_b64 s[98:99], s[0:1]
	v_lshlrev_b32_e32 v240, 2, v114
	global_load_dwordx4 v[106:109], v240, s[64:65]
	global_load_dwordx4 v[110:113], v240, s[44:45]
	global_load_dwordx4 v[114:117], v240, s[64:65] offset:16
	global_load_dwordx4 v[118:121], v240, s[44:45] offset:16
	s_mov_b64 exec, s[98:99]
	ds_bpermute_b32 v96, v90, v84
	ds_bpermute_b32 v100, v90, v80
	ds_bpermute_b32 v97, v90, v85
	ds_bpermute_b32 v101, v90, v81
	ds_bpermute_b32 v94, v90, v86
	s_waitcnt lgkmcnt(0)
	ds_bpermute_b32 v104, v90, v82
	ds_bpermute_b32 v95, v90, v87
	ds_bpermute_b32 v105, v90, v83
	s_and_saveexec_b64 s[28:29], s[0:1]
	s_cbranch_execz .LBB0_937
	s_waitcnt vmcnt(0)
	v_pk_mul_f32 v[90:91], v[86:87], v[108:109]
	v_pk_mul_f32 v[92:93], v[84:85], v[106:107]
	v_pk_mul_f32 v[98:99], v[110:111], v[96:97]
	s_waitcnt lgkmcnt(1)
	v_pk_mul_f32 v[102:103], v[112:113], v[94:95]
	v_pk_mul_f32 v[94:95], v[82:83], v[116:117]
	v_pk_mul_f32 v[96:97], v[80:81], v[114:115]
	v_pk_mul_f32 v[100:101], v[118:119], v[100:101]
	s_waitcnt lgkmcnt(0)
	v_pk_mul_f32 v[104:105], v[120:121], v[104:105]
	s_and_saveexec_b64 s[30:31], s[4:5]
	s_xor_b64 s[30:31], exec, s[30:31]
	v_pk_add_f32 v[86:87], v[90:91], v[102:103]
	v_pk_add_f32 v[84:85], v[92:93], v[98:99]
	v_pk_add_f32 v[82:83], v[94:95], v[104:105]
	v_pk_add_f32 v[80:81], v[96:97], v[100:101]
	s_andn2_saveexec_b64 s[30:31], s[30:31]
	v_sub_f32_e32 v87, v91, v103
	v_sub_f32_e32 v86, v90, v102
	v_sub_f32_e32 v85, v93, v99
	v_sub_f32_e32 v84, v92, v98
	v_sub_f32_e32 v83, v95, v105
	v_sub_f32_e32 v82, v94, v104
	v_sub_f32_e32 v81, v97, v101
	v_sub_f32_e32 v80, v96, v100
	s_or_b64 exec, exec, s[30:31]

.LBB0_940:
	v_cvt_pk_bf16_f32 v84, v84, v85
	v_cvt_pk_bf16_f32 v85, v86, v87
	v_cvt_pk_bf16_f32 v86, v80, v81
	ds_read_b32 v80, v177 offset:192
	v_add_u32_e32 v99, s21, v167
	v_lshlrev_b32_e32 v81, 3, v99
	v_cvt_pk_bf16_f32 v87, v82, v83
	v_and_b32_e32 v98, 0xfff8, v81
	s_waitcnt lgkmcnt(0)
	v_pk_mul_f32 v[78:79], v[78:79], v[80:81] op_sel_hi:[1,0]
	v_pk_mul_f32 v[76:77], v[76:77], v[80:81] op_sel_hi:[1,0]
	v_pk_mul_f32 v[74:75], v[74:75], v[80:81] op_sel_hi:[1,0]
	s_and_b64 vcc, exec, s[8:9]
	v_pk_mul_f32 v[72:73], v[72:73], v[80:81] op_sel_hi:[1,0]
	global_store_dwordx4 v[88:89], v[84:87], off offset:256
	s_cbranch_vccnz .LBB0_948
	v_and_b32_e32 v82, 64, v176
	v_xor_b32_e32 v81, 16, v176
	v_add_u32_e32 v82, 64, v82
	v_cmp_lt_i32_e32 vcc, v81, v82
	s_nop 1
	v_cndmask_b32_e32 v81, v176, v81, vcc
	v_lshlrev_b32_e32 v81, 2, v81
	s_and_saveexec_b64 s[98:99], s[0:1]
	v_lshlrev_b32_e32 v240, 2, v98
	global_load_dwordx4 v[100:103], v240, s[64:65]
	global_load_dwordx4 v[104:107], v240, s[44:45]
	global_load_dwordx4 v[108:111], v240, s[64:65] offset:16
	global_load_dwordx4 v[112:115], v240, s[44:45] offset:16
	s_mov_b64 exec, s[98:99]
	ds_bpermute_b32 v88, v81, v76
	ds_bpermute_b32 v92, v81, v72
	ds_bpermute_b32 v89, v81, v77
	ds_bpermute_b32 v93, v81, v73
	ds_bpermute_b32 v86, v81, v78
	ds_bpermute_b32 v96, v81, v74
	ds_bpermute_b32 v87, v81, v79
	ds_bpermute_b32 v97, v81, v75
	s_and_saveexec_b64 s[28:29], s[0:1]
	s_cbranch_execz .LBB0_947
	s_waitcnt vmcnt(0)
	v_pk_mul_f32 v[82:83], v[78:79], v[102:103]
	v_pk_mul_f32 v[84:85], v[76:77], v[100:101]
	s_waitcnt lgkmcnt(5)
	v_pk_mul_f32 v[90:91], v[104:105], v[88:89]
	s_waitcnt lgkmcnt(1)
	v_pk_mul_f32 v[94:95], v[106:107], v[86:87]
	v_pk_mul_f32 v[86:87], v[74:75], v[110:111]
	v_pk_mul_f32 v[88:89], v[72:73], v[108:109]
	v_pk_mul_f32 v[92:93], v[112:113], v[92:93]
	s_waitcnt lgkmcnt(0)
	v_pk_mul_f32 v[96:97], v[114:115], v[96:97]
	s_and_saveexec_b64 s[30:31], s[4:5]
	s_xor_b64 s[30:31], exec, s[30:31]
	v_pk_add_f32 v[78:79], v[82:83], v[94:95]
	v_pk_add_f32 v[76:77], v[84:85], v[90:91]
	v_pk_add_f32 v[74:75], v[86:87], v[96:97]
	v_pk_add_f32 v[72:73], v[88:89], v[92:93]
	s_andn2_saveexec_b64 s[30:31], s[30:31]
	v_sub_f32_e32 v79, v83, v95
	v_sub_f32_e32 v78, v82, v94
	v_sub_f32_e32 v77, v85, v91
	v_sub_f32_e32 v76, v84, v90
	v_sub_f32_e32 v75, v87, v97
	v_sub_f32_e32 v74, v86, v96
	v_sub_f32_e32 v73, v89, v93
	v_sub_f32_e32 v72, v88, v92
	s_or_b64 exec, exec, s[30:31]

.LBB0_950:
	v_cvt_pk_bf16_f32 v76, v76, v77
	v_cvt_pk_bf16_f32 v77, v78, v79
	v_cvt_pk_bf16_f32 v78, v72, v73
	v_mov_b64_e32 v[72:73], s[76:77]
	v_mov_b32_e32 v81, v80
	v_cvt_pk_bf16_f32 v79, v74, v75
	v_mad_i64_i32 v[72:73], s[28:29], v99, s51, v[72:73]
	v_mov_b32_e32 v74, v80
	v_mov_b32_e32 v75, v80
	v_lshl_add_u64 v[72:73], v[144:145], 1, v[72:73]
	v_pk_mul_f32 v[70:71], v[70:71], v[74:75]
	v_pk_mul_f32 v[68:69], v[68:69], v[80:81]
	v_pk_mul_f32 v[66:67], v[66:67], v[74:75]
	s_and_b64 vcc, exec, s[8:9]
	v_pk_mul_f32 v[64:65], v[64:65], v[80:81]
	global_store_dwordx4 v[72:73], v[76:79], off
	s_cbranch_vccnz .LBB0_958
	v_and_b32_e32 v75, 64, v176
	v_xor_b32_e32 v74, 16, v176
	v_add_u32_e32 v75, 64, v75
	v_cmp_lt_i32_e32 vcc, v74, v75
	s_nop 1
	v_cndmask_b32_e32 v74, v176, v74, vcc
	v_lshlrev_b32_e32 v74, 2, v74
	s_and_saveexec_b64 s[98:99], s[0:1]
	v_lshlrev_b32_e32 v240, 2, v98
	global_load_dwordx4 v[90:93], v240, s[64:65]
	global_load_dwordx4 v[94:97], v240, s[44:45]
	global_load_dwordx4 v[98:101], v240, s[64:65] offset:16
	global_load_dwordx4 v[102:105], v240, s[44:45] offset:16
	s_mov_b64 exec, s[98:99]
	ds_bpermute_b32 v80, v74, v68
	ds_bpermute_b32 v84, v74, v64
	ds_bpermute_b32 v81, v74, v69
	ds_bpermute_b32 v85, v74, v65
	ds_bpermute_b32 v78, v74, v70
	s_waitcnt lgkmcnt(0)
	ds_bpermute_b32 v88, v74, v66
	ds_bpermute_b32 v79, v74, v71
	ds_bpermute_b32 v89, v74, v67
	s_and_saveexec_b64 s[28:29], s[0:1]
	s_cbranch_execz .LBB0_957
	s_waitcnt vmcnt(0)
	v_pk_mul_f32 v[74:75], v[70:71], v[92:93]
	v_pk_mul_f32 v[76:77], v[68:69], v[90:91]
	v_pk_mul_f32 v[82:83], v[94:95], v[80:81]
	s_waitcnt lgkmcnt(1)
	v_pk_mul_f32 v[86:87], v[96:97], v[78:79]
	v_pk_mul_f32 v[78:79], v[66:67], v[100:101]
	v_pk_mul_f32 v[80:81], v[64:65], v[98:99]
	v_pk_mul_f32 v[84:85], v[102:103], v[84:85]
	s_waitcnt lgkmcnt(0)
	v_pk_mul_f32 v[88:89], v[104:105], v[88:89]
	s_and_saveexec_b64 s[30:31], s[4:5]
	s_xor_b64 s[30:31], exec, s[30:31]
	v_pk_add_f32 v[70:71], v[74:75], v[86:87]
	v_pk_add_f32 v[68:69], v[76:77], v[82:83]
	v_pk_add_f32 v[66:67], v[78:79], v[88:89]
	v_pk_add_f32 v[64:65], v[80:81], v[84:85]
	s_andn2_saveexec_b64 s[30:31], s[30:31]
	v_sub_f32_e32 v71, v75, v87
	v_sub_f32_e32 v70, v74, v86
	v_sub_f32_e32 v69, v77, v83
	v_sub_f32_e32 v68, v76, v82
	v_sub_f32_e32 v67, v79, v89
	v_sub_f32_e32 v66, v78, v88
	v_sub_f32_e32 v65, v81, v85
	v_sub_f32_e32 v64, v80, v84
	s_or_b64 exec, exec, s[30:31]

.LBB0_960:
	v_cvt_pk_bf16_f32 v68, v68, v69
	v_cvt_pk_bf16_f32 v69, v70, v71
	v_cvt_pk_bf16_f32 v70, v64, v65
	ds_read_b32 v64, v177 offset:512
	v_add_u32_e32 v83, s21, v168
	v_lshlrev_b32_e32 v65, 3, v83
	v_cvt_pk_bf16_f32 v71, v66, v67
	v_and_b32_e32 v82, 0xfe78, v65
	s_waitcnt lgkmcnt(0)
	v_pk_mul_f32 v[62:63], v[62:63], v[64:65] op_sel_hi:[1,0]
	v_pk_mul_f32 v[60:61], v[60:61], v[64:65] op_sel_hi:[1,0]
	v_pk_mul_f32 v[58:59], v[58:59], v[64:65] op_sel_hi:[1,0]
	s_and_b64 vcc, exec, s[8:9]
	v_pk_mul_f32 v[56:57], v[56:57], v[64:65] op_sel_hi:[1,0]
	global_store_dwordx4 v[72:73], v[68:71], off offset:256
	s_cbranch_vccnz .LBB0_968
	v_and_b32_e32 v66, 64, v176
	v_xor_b32_e32 v65, 16, v176
	v_add_u32_e32 v66, 64, v66
	v_cmp_lt_i32_e32 vcc, v65, v66
	s_nop 1
	v_cndmask_b32_e32 v65, v176, v65, vcc
	v_lshlrev_b32_e32 v65, 2, v65
	s_and_saveexec_b64 s[98:99], s[0:1]
	v_lshlrev_b32_e32 v240, 2, v82
	global_load_dwordx4 v[84:87], v240, s[64:65]
	global_load_dwordx4 v[88:91], v240, s[44:45]
	global_load_dwordx4 v[92:95], v240, s[64:65] offset:16
	global_load_dwordx4 v[96:99], v240, s[44:45] offset:16
	s_mov_b64 exec, s[98:99]
	ds_bpermute_b32 v72, v65, v60
	ds_bpermute_b32 v76, v65, v56
	ds_bpermute_b32 v73, v65, v61
	ds_bpermute_b32 v77, v65, v57
	ds_bpermute_b32 v70, v65, v62
	ds_bpermute_b32 v80, v65, v58
	ds_bpermute_b32 v71, v65, v63
	ds_bpermute_b32 v81, v65, v59
	s_and_saveexec_b64 s[28:29], s[0:1]
	s_cbranch_execz .LBB0_967
	s_waitcnt vmcnt(0)
	v_pk_mul_f32 v[66:67], v[62:63], v[86:87]
	v_pk_mul_f32 v[68:69], v[60:61], v[84:85]
	s_waitcnt lgkmcnt(5)
	v_pk_mul_f32 v[74:75], v[88:89], v[72:73]
	s_waitcnt lgkmcnt(1)
	v_pk_mul_f32 v[78:79], v[90:91], v[70:71]
	v_pk_mul_f32 v[70:71], v[58:59], v[94:95]
	v_pk_mul_f32 v[72:73], v[56:57], v[92:93]
	v_pk_mul_f32 v[76:77], v[96:97], v[76:77]
	s_waitcnt lgkmcnt(0)
	v_pk_mul_f32 v[80:81], v[98:99], v[80:81]
	s_and_saveexec_b64 s[30:31], s[4:5]
	s_xor_b64 s[30:31], exec, s[30:31]
	v_pk_add_f32 v[62:63], v[66:67], v[78:79]
	v_pk_add_f32 v[60:61], v[68:69], v[74:75]
	v_pk_add_f32 v[58:59], v[70:71], v[80:81]
	v_pk_add_f32 v[56:57], v[72:73], v[76:77]
	s_andn2_saveexec_b64 s[30:31], s[30:31]
	v_sub_f32_e32 v63, v67, v79
	v_sub_f32_e32 v62, v66, v78
	v_sub_f32_e32 v61, v69, v75
	v_sub_f32_e32 v60, v68, v74
	v_sub_f32_e32 v59, v71, v81
	v_sub_f32_e32 v58, v70, v80
	v_sub_f32_e32 v57, v73, v77
	v_sub_f32_e32 v56, v72, v76
	s_or_b64 exec, exec, s[30:31]

.LBB0_970:
	v_cvt_pk_bf16_f32 v60, v60, v61
	v_cvt_pk_bf16_f32 v61, v62, v63
	v_cvt_pk_bf16_f32 v62, v56, v57
	v_mov_b64_e32 v[56:57], s[76:77]
	v_mov_b32_e32 v65, v64
	v_cvt_pk_bf16_f32 v63, v58, v59
	v_mad_i64_i32 v[56:57], s[28:29], v83, s51, v[56:57]
	v_mov_b32_e32 v58, v64
	v_mov_b32_e32 v59, v64
	v_lshl_add_u64 v[56:57], v[144:145], 1, v[56:57]
	v_pk_mul_f32 v[54:55], v[54:55], v[58:59]
	v_pk_mul_f32 v[52:53], v[52:53], v[64:65]
	v_pk_mul_f32 v[50:51], v[50:51], v[58:59]
	s_and_b64 vcc, exec, s[8:9]
	v_pk_mul_f32 v[48:49], v[48:49], v[64:65]
	global_store_dwordx4 v[56:57], v[60:63], off
	s_cbranch_vccnz .LBB0_978
	v_and_b32_e32 v59, 64, v176
	v_xor_b32_e32 v58, 16, v176
	v_add_u32_e32 v59, 64, v59
	v_cmp_lt_i32_e32 vcc, v58, v59
	s_nop 1
	v_cndmask_b32_e32 v58, v176, v58, vcc
	v_lshlrev_b32_e32 v58, 2, v58
	s_and_saveexec_b64 s[98:99], s[0:1]
	v_lshlrev_b32_e32 v240, 2, v82
	global_load_dwordx4 v[74:77], v240, s[64:65]
	global_load_dwordx4 v[78:81], v240, s[44:45]
	global_load_dwordx4 v[82:85], v240, s[64:65] offset:16
	global_load_dwordx4 v[86:89], v240, s[44:45] offset:16
	s_mov_b64 exec, s[98:99]
	ds_bpermute_b32 v64, v58, v52
	ds_bpermute_b32 v68, v58, v48
	ds_bpermute_b32 v65, v58, v53
	ds_bpermute_b32 v69, v58, v49
	ds_bpermute_b32 v62, v58, v54
	s_waitcnt lgkmcnt(0)
	ds_bpermute_b32 v72, v58, v50
	ds_bpermute_b32 v63, v58, v55
	ds_bpermute_b32 v73, v58, v51
	s_and_saveexec_b64 s[28:29], s[0:1]
	s_cbranch_execz .LBB0_977
	s_waitcnt vmcnt(0)
	v_pk_mul_f32 v[58:59], v[54:55], v[76:77]
	v_pk_mul_f32 v[60:61], v[52:53], v[74:75]
	v_pk_mul_f32 v[66:67], v[78:79], v[64:65]
	s_waitcnt lgkmcnt(1)
	v_pk_mul_f32 v[70:71], v[80:81], v[62:63]
	v_pk_mul_f32 v[62:63], v[50:51], v[84:85]
	v_pk_mul_f32 v[64:65], v[48:49], v[82:83]
	v_pk_mul_f32 v[68:69], v[86:87], v[68:69]
	s_waitcnt lgkmcnt(0)
	v_pk_mul_f32 v[72:73], v[88:89], v[72:73]
	s_and_saveexec_b64 s[30:31], s[4:5]
	s_xor_b64 s[30:31], exec, s[30:31]
	v_pk_add_f32 v[54:55], v[58:59], v[70:71]
	v_pk_add_f32 v[52:53], v[60:61], v[66:67]
	v_pk_add_f32 v[50:51], v[62:63], v[72:73]
	v_pk_add_f32 v[48:49], v[64:65], v[68:69]
	s_andn2_saveexec_b64 s[30:31], s[30:31]
	v_sub_f32_e32 v55, v59, v71
	v_sub_f32_e32 v54, v58, v70
	v_sub_f32_e32 v53, v61, v67
	v_sub_f32_e32 v52, v60, v66
	v_sub_f32_e32 v51, v63, v73
	v_sub_f32_e32 v50, v62, v72
	v_sub_f32_e32 v49, v65, v69
	v_sub_f32_e32 v48, v64, v68
	s_or_b64 exec, exec, s[30:31]

.LBB0_980:
	v_cvt_pk_bf16_f32 v52, v52, v53
	v_cvt_pk_bf16_f32 v53, v54, v55
	v_cvt_pk_bf16_f32 v54, v48, v49
	ds_read_b32 v48, v177 offset:576
	v_add_u32_e32 v67, s21, v169
	v_lshlrev_b32_e32 v49, 3, v67
	v_cvt_pk_bf16_f32 v55, v50, v51
	v_and_b32_e32 v66, 0xfef8, v49
	s_waitcnt lgkmcnt(0)
	v_pk_mul_f32 v[46:47], v[46:47], v[48:49] op_sel_hi:[1,0]
	v_pk_mul_f32 v[44:45], v[44:45], v[48:49] op_sel_hi:[1,0]
	v_pk_mul_f32 v[42:43], v[42:43], v[48:49] op_sel_hi:[1,0]
	s_and_b64 vcc, exec, s[8:9]
	v_pk_mul_f32 v[40:41], v[40:41], v[48:49] op_sel_hi:[1,0]
	global_store_dwordx4 v[56:57], v[52:55], off offset:256
	s_cbranch_vccnz .LBB0_988
	v_and_b32_e32 v50, 64, v176
	v_xor_b32_e32 v49, 16, v176
	v_add_u32_e32 v50, 64, v50
	v_cmp_lt_i32_e32 vcc, v49, v50
	s_nop 1
	v_cndmask_b32_e32 v49, v176, v49, vcc
	v_lshlrev_b32_e32 v49, 2, v49
	s_and_saveexec_b64 s[98:99], s[0:1]
	v_lshlrev_b32_e32 v240, 2, v66
	global_load_dwordx4 v[68:71], v240, s[64:65]
	global_load_dwordx4 v[72:75], v240, s[44:45]
	global_load_dwordx4 v[76:79], v240, s[64:65] offset:16
	global_load_dwordx4 v[80:83], v240, s[44:45] offset:16
	s_mov_b64 exec, s[98:99]
	ds_bpermute_b32 v56, v49, v44
	ds_bpermute_b32 v60, v49, v40
	ds_bpermute_b32 v57, v49, v45
	ds_bpermute_b32 v61, v49, v41
	ds_bpermute_b32 v54, v49, v46
	ds_bpermute_b32 v64, v49, v42
	ds_bpermute_b32 v55, v49, v47
	ds_bpermute_b32 v65, v49, v43
	s_and_saveexec_b64 s[28:29], s[0:1]
	s_cbranch_execz .LBB0_987
	s_waitcnt vmcnt(0)
	v_pk_mul_f32 v[50:51], v[46:47], v[70:71]
	v_pk_mul_f32 v[52:53], v[44:45], v[68:69]
	s_waitcnt lgkmcnt(5)
	v_pk_mul_f32 v[58:59], v[72:73], v[56:57]
	s_waitcnt lgkmcnt(1)
	v_pk_mul_f32 v[62:63], v[74:75], v[54:55]
	v_pk_mul_f32 v[54:55], v[42:43], v[78:79]
	v_pk_mul_f32 v[56:57], v[40:41], v[76:77]
	v_pk_mul_f32 v[60:61], v[80:81], v[60:61]
	s_waitcnt lgkmcnt(0)
	v_pk_mul_f32 v[64:65], v[82:83], v[64:65]
	s_and_saveexec_b64 s[30:31], s[4:5]
	s_xor_b64 s[30:31], exec, s[30:31]
	v_pk_add_f32 v[46:47], v[50:51], v[62:63]
	v_pk_add_f32 v[44:45], v[52:53], v[58:59]
	v_pk_add_f32 v[42:43], v[54:55], v[64:65]
	v_pk_add_f32 v[40:41], v[56:57], v[60:61]
	s_andn2_saveexec_b64 s[30:31], s[30:31]
	v_sub_f32_e32 v47, v51, v63
	v_sub_f32_e32 v46, v50, v62
	v_sub_f32_e32 v45, v53, v59
	v_sub_f32_e32 v44, v52, v58
	v_sub_f32_e32 v43, v55, v65
	v_sub_f32_e32 v42, v54, v64
	v_sub_f32_e32 v41, v57, v61
	v_sub_f32_e32 v40, v56, v60
	s_or_b64 exec, exec, s[30:31]

.LBB0_990:
	v_cvt_pk_bf16_f32 v44, v44, v45
	v_cvt_pk_bf16_f32 v45, v46, v47
	v_cvt_pk_bf16_f32 v46, v40, v41
	v_mov_b64_e32 v[40:41], s[76:77]
	v_mov_b32_e32 v49, v48
	v_cvt_pk_bf16_f32 v47, v42, v43
	v_mad_i64_i32 v[40:41], s[28:29], v67, s51, v[40:41]
	v_mov_b32_e32 v42, v48
	v_mov_b32_e32 v43, v48
	v_lshl_add_u64 v[40:41], v[144:145], 1, v[40:41]
	v_pk_mul_f32 v[38:39], v[38:39], v[42:43]
	v_pk_mul_f32 v[36:37], v[36:37], v[48:49]
	v_pk_mul_f32 v[34:35], v[34:35], v[42:43]
	s_and_b64 vcc, exec, s[8:9]
	v_pk_mul_f32 v[32:33], v[32:33], v[48:49]
	global_store_dwordx4 v[40:41], v[44:47], off
	s_cbranch_vccnz .LBB0_998
	v_and_b32_e32 v43, 64, v176
	v_xor_b32_e32 v42, 16, v176
	v_add_u32_e32 v43, 64, v43
	v_cmp_lt_i32_e32 vcc, v42, v43
	s_nop 1
	v_cndmask_b32_e32 v42, v176, v42, vcc
	v_lshlrev_b32_e32 v42, 2, v42
	s_and_saveexec_b64 s[98:99], s[0:1]
	v_lshlrev_b32_e32 v240, 2, v66
	global_load_dwordx4 v[58:61], v240, s[64:65]
	global_load_dwordx4 v[62:65], v240, s[44:45]
	global_load_dwordx4 v[66:69], v240, s[64:65] offset:16
	global_load_dwordx4 v[70:73], v240, s[44:45] offset:16
	s_mov_b64 exec, s[98:99]
	ds_bpermute_b32 v48, v42, v36
	ds_bpermute_b32 v52, v42, v32
	ds_bpermute_b32 v49, v42, v37
	ds_bpermute_b32 v53, v42, v33
	ds_bpermute_b32 v46, v42, v38
	s_waitcnt lgkmcnt(0)
	ds_bpermute_b32 v56, v42, v34
	ds_bpermute_b32 v47, v42, v39
	ds_bpermute_b32 v57, v42, v35
	s_and_saveexec_b64 s[28:29], s[0:1]
	s_cbranch_execz .LBB0_997
	s_waitcnt vmcnt(0)
	v_pk_mul_f32 v[42:43], v[38:39], v[60:61]
	v_pk_mul_f32 v[44:45], v[36:37], v[58:59]
	v_pk_mul_f32 v[50:51], v[62:63], v[48:49]
	s_waitcnt lgkmcnt(1)
	v_pk_mul_f32 v[54:55], v[64:65], v[46:47]
	v_pk_mul_f32 v[46:47], v[34:35], v[68:69]
	v_pk_mul_f32 v[48:49], v[32:33], v[66:67]
	v_pk_mul_f32 v[52:53], v[70:71], v[52:53]
	s_waitcnt lgkmcnt(0)
	v_pk_mul_f32 v[56:57], v[72:73], v[56:57]
	s_and_saveexec_b64 s[30:31], s[4:5]
	s_xor_b64 s[30:31], exec, s[30:31]
	v_pk_add_f32 v[38:39], v[42:43], v[54:55]
	v_pk_add_f32 v[36:37], v[44:45], v[50:51]
	v_pk_add_f32 v[34:35], v[46:47], v[56:57]
	v_pk_add_f32 v[32:33], v[48:49], v[52:53]
	s_andn2_saveexec_b64 s[30:31], s[30:31]
	v_sub_f32_e32 v39, v43, v55
	v_sub_f32_e32 v38, v42, v54
	v_sub_f32_e32 v37, v45, v51
	v_sub_f32_e32 v36, v44, v50
	v_sub_f32_e32 v35, v47, v57
	v_sub_f32_e32 v34, v46, v56
	v_sub_f32_e32 v33, v49, v53
	v_sub_f32_e32 v32, v48, v52
	s_or_b64 exec, exec, s[30:31]

.LBB0_1000:
	v_cvt_pk_bf16_f32 v36, v36, v37
	v_cvt_pk_bf16_f32 v37, v38, v39
	v_cvt_pk_bf16_f32 v38, v32, v33
	ds_read_b32 v32, v177 offset:640
	v_add_u32_e32 v51, s21, v170
	v_lshlrev_b32_e32 v33, 3, v51
	v_cvt_pk_bf16_f32 v39, v34, v35
	v_and_b32_e32 v50, 0xff78, v33
	s_waitcnt lgkmcnt(0)
	v_pk_mul_f32 v[30:31], v[30:31], v[32:33] op_sel_hi:[1,0]
	v_pk_mul_f32 v[28:29], v[28:29], v[32:33] op_sel_hi:[1,0]
	v_pk_mul_f32 v[26:27], v[26:27], v[32:33] op_sel_hi:[1,0]
	s_and_b64 vcc, exec, s[8:9]
	v_pk_mul_f32 v[24:25], v[24:25], v[32:33] op_sel_hi:[1,0]
	global_store_dwordx4 v[40:41], v[36:39], off offset:256
	s_cbranch_vccnz .LBB0_1008
	v_and_b32_e32 v34, 64, v176
	v_xor_b32_e32 v33, 16, v176
	v_add_u32_e32 v34, 64, v34
	v_cmp_lt_i32_e32 vcc, v33, v34
	s_nop 1
	v_cndmask_b32_e32 v33, v176, v33, vcc
	v_lshlrev_b32_e32 v33, 2, v33
	s_and_saveexec_b64 s[98:99], s[0:1]
	v_lshlrev_b32_e32 v240, 2, v50
	global_load_dwordx4 v[52:55], v240, s[64:65]
	global_load_dwordx4 v[56:59], v240, s[44:45]
	global_load_dwordx4 v[60:63], v240, s[64:65] offset:16
	global_load_dwordx4 v[64:67], v240, s[44:45] offset:16
	s_mov_b64 exec, s[98:99]
	ds_bpermute_b32 v40, v33, v28
	ds_bpermute_b32 v44, v33, v24
	ds_bpermute_b32 v41, v33, v29
	ds_bpermute_b32 v45, v33, v25
	ds_bpermute_b32 v38, v33, v30
	ds_bpermute_b32 v48, v33, v26
	ds_bpermute_b32 v39, v33, v31
	ds_bpermute_b32 v49, v33, v27
	s_and_saveexec_b64 s[28:29], s[0:1]
	s_cbranch_execz .LBB0_1007
	s_waitcnt vmcnt(0)
	v_pk_mul_f32 v[34:35], v[30:31], v[54:55]
	v_pk_mul_f32 v[36:37], v[28:29], v[52:53]
	s_waitcnt lgkmcnt(5)
	v_pk_mul_f32 v[42:43], v[56:57], v[40:41]
	s_waitcnt lgkmcnt(1)
	v_pk_mul_f32 v[46:47], v[58:59], v[38:39]
	v_pk_mul_f32 v[38:39], v[26:27], v[62:63]
	v_pk_mul_f32 v[40:41], v[24:25], v[60:61]
	v_pk_mul_f32 v[44:45], v[64:65], v[44:45]
	s_waitcnt lgkmcnt(0)
	v_pk_mul_f32 v[48:49], v[66:67], v[48:49]
	s_and_saveexec_b64 s[30:31], s[4:5]
	s_xor_b64 s[30:31], exec, s[30:31]
	v_pk_add_f32 v[30:31], v[34:35], v[46:47]
	v_pk_add_f32 v[28:29], v[36:37], v[42:43]
	v_pk_add_f32 v[26:27], v[38:39], v[48:49]
	v_pk_add_f32 v[24:25], v[40:41], v[44:45]
	s_andn2_saveexec_b64 s[30:31], s[30:31]
	v_sub_f32_e32 v31, v35, v47
	v_sub_f32_e32 v30, v34, v46
	v_sub_f32_e32 v29, v37, v43
	v_sub_f32_e32 v28, v36, v42
	v_sub_f32_e32 v27, v39, v49
	v_sub_f32_e32 v26, v38, v48
	v_sub_f32_e32 v25, v41, v45
	v_sub_f32_e32 v24, v40, v44
	s_or_b64 exec, exec, s[30:31]

.LBB0_1010:
	v_cvt_pk_bf16_f32 v28, v28, v29
	v_cvt_pk_bf16_f32 v29, v30, v31
	v_cvt_pk_bf16_f32 v30, v24, v25
	v_mov_b64_e32 v[24:25], s[76:77]
	v_mov_b32_e32 v33, v32
	v_cvt_pk_bf16_f32 v31, v26, v27
	v_mad_i64_i32 v[24:25], s[28:29], v51, s51, v[24:25]
	v_mov_b32_e32 v26, v32
	v_mov_b32_e32 v27, v32
	v_lshl_add_u64 v[24:25], v[144:145], 1, v[24:25]
	v_pk_mul_f32 v[22:23], v[22:23], v[26:27]
	v_pk_mul_f32 v[20:21], v[20:21], v[32:33]
	v_pk_mul_f32 v[18:19], v[18:19], v[26:27]
	s_and_b64 vcc, exec, s[8:9]
	v_pk_mul_f32 v[16:17], v[16:17], v[32:33]
	global_store_dwordx4 v[24:25], v[28:31], off
	s_cbranch_vccnz .LBB0_1018
	v_and_b32_e32 v27, 64, v176
	v_xor_b32_e32 v26, 16, v176
	v_add_u32_e32 v27, 64, v27
	v_cmp_lt_i32_e32 vcc, v26, v27
	s_nop 1
	v_cndmask_b32_e32 v26, v176, v26, vcc
	v_lshlrev_b32_e32 v26, 2, v26
	s_and_saveexec_b64 s[98:99], s[0:1]
	v_lshlrev_b32_e32 v240, 2, v50
	global_load_dwordx4 v[42:45], v240, s[64:65]
	global_load_dwordx4 v[46:49], v240, s[44:45]
	global_load_dwordx4 v[50:53], v240, s[64:65] offset:16
	global_load_dwordx4 v[54:57], v240, s[44:45] offset:16
	s_mov_b64 exec, s[98:99]
	ds_bpermute_b32 v32, v26, v20
	ds_bpermute_b32 v36, v26, v16
	ds_bpermute_b32 v33, v26, v21
	ds_bpermute_b32 v37, v26, v17
	ds_bpermute_b32 v30, v26, v22
	s_waitcnt lgkmcnt(0)
	ds_bpermute_b32 v40, v26, v18
	ds_bpermute_b32 v31, v26, v23
	ds_bpermute_b32 v41, v26, v19
	s_and_saveexec_b64 s[28:29], s[0:1]
	s_cbranch_execz .LBB0_1017
	s_waitcnt vmcnt(0)
	v_pk_mul_f32 v[26:27], v[22:23], v[44:45]
	v_pk_mul_f32 v[28:29], v[20:21], v[42:43]
	v_pk_mul_f32 v[34:35], v[46:47], v[32:33]
	s_waitcnt lgkmcnt(1)
	v_pk_mul_f32 v[38:39], v[48:49], v[30:31]
	v_pk_mul_f32 v[30:31], v[18:19], v[52:53]
	v_pk_mul_f32 v[32:33], v[16:17], v[50:51]
	v_pk_mul_f32 v[36:37], v[54:55], v[36:37]
	s_waitcnt lgkmcnt(0)
	v_pk_mul_f32 v[40:41], v[56:57], v[40:41]
	s_and_saveexec_b64 s[30:31], s[4:5]
	s_xor_b64 s[30:31], exec, s[30:31]
	v_pk_add_f32 v[22:23], v[26:27], v[38:39]
	v_pk_add_f32 v[20:21], v[28:29], v[34:35]
	v_pk_add_f32 v[18:19], v[30:31], v[40:41]
	v_pk_add_f32 v[16:17], v[32:33], v[36:37]
	s_andn2_saveexec_b64 s[30:31], s[30:31]
	v_sub_f32_e32 v23, v27, v39
	v_sub_f32_e32 v22, v26, v38
	v_sub_f32_e32 v21, v29, v35
	v_sub_f32_e32 v20, v28, v34
	v_sub_f32_e32 v19, v31, v41
	v_sub_f32_e32 v18, v30, v40
	v_sub_f32_e32 v17, v33, v37
	v_sub_f32_e32 v16, v32, v36
	s_or_b64 exec, exec, s[30:31]

.LBB0_1020:
	v_cvt_pk_bf16_f32 v20, v20, v21
	v_cvt_pk_bf16_f32 v21, v22, v23
	v_cvt_pk_bf16_f32 v22, v16, v17
	ds_read_b32 v16, v177 offset:704
	v_add_u32_e32 v35, s21, v171
	v_lshlrev_b32_e32 v17, 3, v35
	v_cvt_pk_bf16_f32 v23, v18, v19
	v_and_b32_e32 v34, 0xfff8, v17
	s_waitcnt lgkmcnt(0)
	v_pk_mul_f32 v[14:15], v[14:15], v[16:17] op_sel_hi:[1,0]
	v_pk_mul_f32 v[12:13], v[12:13], v[16:17] op_sel_hi:[1,0]
	v_pk_mul_f32 v[10:11], v[10:11], v[16:17] op_sel_hi:[1,0]
	s_and_b64 vcc, exec, s[8:9]
	v_pk_mul_f32 v[8:9], v[8:9], v[16:17] op_sel_hi:[1,0]
	global_store_dwordx4 v[24:25], v[20:23], off offset:256
	s_cbranch_vccnz .LBB0_1028
	v_and_b32_e32 v18, 64, v176
	v_xor_b32_e32 v17, 16, v176
	v_add_u32_e32 v18, 64, v18
	v_cmp_lt_i32_e32 vcc, v17, v18
	s_nop 1
	v_cndmask_b32_e32 v17, v176, v17, vcc
	v_lshlrev_b32_e32 v17, 2, v17
	s_and_saveexec_b64 s[98:99], s[0:1]
	v_lshlrev_b32_e32 v240, 2, v34
	global_load_dwordx4 v[36:39], v240, s[64:65]
	global_load_dwordx4 v[40:43], v240, s[44:45]
	global_load_dwordx4 v[44:47], v240, s[64:65] offset:16
	global_load_dwordx4 v[48:51], v240, s[44:45] offset:16
	s_mov_b64 exec, s[98:99]
	ds_bpermute_b32 v24, v17, v12
	ds_bpermute_b32 v28, v17, v8
	ds_bpermute_b32 v25, v17, v13
	ds_bpermute_b32 v29, v17, v9
	ds_bpermute_b32 v22, v17, v14
	ds_bpermute_b32 v32, v17, v10
	ds_bpermute_b32 v23, v17, v15
	ds_bpermute_b32 v33, v17, v11
	s_and_saveexec_b64 s[28:29], s[0:1]
	s_cbranch_execz .LBB0_1027
	s_waitcnt vmcnt(0)
	v_pk_mul_f32 v[18:19], v[14:15], v[38:39]
	v_pk_mul_f32 v[20:21], v[12:13], v[36:37]
	s_waitcnt lgkmcnt(5)
	v_pk_mul_f32 v[26:27], v[40:41], v[24:25]
	s_waitcnt lgkmcnt(1)
	v_pk_mul_f32 v[30:31], v[42:43], v[22:23]
	v_pk_mul_f32 v[22:23], v[10:11], v[46:47]
	v_pk_mul_f32 v[24:25], v[8:9], v[44:45]
	v_pk_mul_f32 v[28:29], v[48:49], v[28:29]
	s_waitcnt lgkmcnt(0)
	v_pk_mul_f32 v[32:33], v[50:51], v[32:33]
	s_and_saveexec_b64 s[30:31], s[4:5]
	s_xor_b64 s[30:31], exec, s[30:31]
	v_pk_add_f32 v[14:15], v[18:19], v[30:31]
	v_pk_add_f32 v[12:13], v[20:21], v[26:27]
	v_pk_add_f32 v[10:11], v[22:23], v[32:33]
	v_pk_add_f32 v[8:9], v[24:25], v[28:29]
	s_andn2_saveexec_b64 s[30:31], s[30:31]
	v_sub_f32_e32 v15, v19, v31
	v_sub_f32_e32 v14, v18, v30
	v_sub_f32_e32 v13, v21, v27
	v_sub_f32_e32 v12, v20, v26
	v_sub_f32_e32 v11, v23, v33
	v_sub_f32_e32 v10, v22, v32
	v_sub_f32_e32 v9, v25, v29
	v_sub_f32_e32 v8, v24, v28
	s_or_b64 exec, exec, s[30:31]

.LBB0_1030:
	v_cvt_pk_bf16_f32 v12, v12, v13
	v_cvt_pk_bf16_f32 v13, v14, v15
	v_cvt_pk_bf16_f32 v14, v8, v9
	v_mov_b64_e32 v[8:9], s[76:77]
	v_mov_b32_e32 v17, v16
	v_cvt_pk_bf16_f32 v15, v10, v11
	v_mad_i64_i32 v[8:9], s[28:29], v35, s51, v[8:9]
	v_mov_b32_e32 v10, v16
	v_mov_b32_e32 v11, v16
	v_lshl_add_u64 v[8:9], v[144:145], 1, v[8:9]
	v_pk_mul_f32 v[6:7], v[6:7], v[10:11]
	v_pk_mul_f32 v[4:5], v[4:5], v[16:17]
	v_pk_mul_f32 v[2:3], v[2:3], v[10:11]
	s_and_b64 vcc, exec, s[8:9]
	v_pk_mul_f32 v[0:1], v[0:1], v[16:17]
	global_store_dwordx4 v[8:9], v[12:15], off
	s_cbranch_vccnz .LBB0_1038
	v_and_b32_e32 v11, 64, v176
	v_xor_b32_e32 v10, 16, v176
	v_add_u32_e32 v11, 64, v11
	v_cmp_lt_i32_e32 vcc, v10, v11
	s_nop 1
	v_cndmask_b32_e32 v10, v176, v10, vcc
	v_lshlrev_b32_e32 v10, 2, v10
	s_and_saveexec_b64 s[98:99], s[0:1]
	v_lshlrev_b32_e32 v240, 2, v34
	global_load_dwordx4 v[26:29], v240, s[64:65]
	global_load_dwordx4 v[30:33], v240, s[44:45]
	global_load_dwordx4 v[34:37], v240, s[64:65] offset:16
	global_load_dwordx4 v[38:41], v240, s[44:45] offset:16
	s_mov_b64 exec, s[98:99]
	ds_bpermute_b32 v16, v10, v4
	ds_bpermute_b32 v20, v10, v0
	ds_bpermute_b32 v17, v10, v5
	ds_bpermute_b32 v21, v10, v1
	ds_bpermute_b32 v14, v10, v6
	s_waitcnt lgkmcnt(0)
	ds_bpermute_b32 v24, v10, v2
	ds_bpermute_b32 v15, v10, v7
	ds_bpermute_b32 v25, v10, v3
	s_and_saveexec_b64 s[8:9], s[0:1]
	s_cbranch_execz .LBB0_1037
	s_waitcnt vmcnt(0)
	v_pk_mul_f32 v[10:11], v[6:7], v[28:29]
	v_pk_mul_f32 v[12:13], v[4:5], v[26:27]
	v_pk_mul_f32 v[18:19], v[30:31], v[16:17]
	s_waitcnt lgkmcnt(1)
	v_pk_mul_f32 v[22:23], v[32:33], v[14:15]
	v_pk_mul_f32 v[14:15], v[2:3], v[36:37]
	v_pk_mul_f32 v[16:17], v[0:1], v[34:35]
	v_pk_mul_f32 v[20:21], v[38:39], v[20:21]
	s_waitcnt lgkmcnt(0)
	v_pk_mul_f32 v[24:25], v[40:41], v[24:25]
	s_and_saveexec_b64 s[28:29], s[4:5]
	s_xor_b64 s[28:29], exec, s[28:29]
	v_pk_add_f32 v[6:7], v[10:11], v[22:23]
	v_pk_add_f32 v[4:5], v[12:13], v[18:19]
	v_pk_add_f32 v[2:3], v[14:15], v[24:25]
	v_pk_add_f32 v[0:1], v[16:17], v[20:21]
	s_andn2_saveexec_b64 s[28:29], s[28:29]
	v_sub_f32_e32 v7, v11, v23
	v_sub_f32_e32 v6, v10, v22
	v_sub_f32_e32 v5, v13, v19
	v_sub_f32_e32 v4, v12, v18
	v_sub_f32_e32 v3, v15, v25
	v_sub_f32_e32 v2, v14, v24
	v_sub_f32_e32 v1, v17, v21
	v_sub_f32_e32 v0, v16, v20
	s_or_b64 exec, exec, s[28:29]
